# rstd_table: per-row integer-division SO.next replaced by a lane table of the units' M-tile indices (written in the scalar unit-count loop, read with v_readlane); padding keeps every GEMM loop at its p
# speedup vs baseline: 1.0012x; 1.0012x over previous
.LBB0_558:
	s_waitcnt lgkmcnt(0)
	v_mov_b64_e32 v[2:3], s[94:95]
	v_cmp_ge_i64_e32 vcc, s[0:1], v[2:3]
	s_cbranch_vccnz .LBB0_557
	s_ashr_i32 s5, s0, 31
	s_lshr_b32 s5, s5, 29
	s_add_i32 s5, s0, s5
	s_ashr_i32 s6, s5, 3
	s_and_b32 s5, s5, -8
	s_sub_i32 s5, s0, s5
	s_cmp_lt_i32 s5, 0
	s_cselect_b32 s7, s92, s57
	s_mul_i32 s5, s7, s5
	s_add_i32 s5, s5, s6
	s_abs_i32 s7, s5
	s_mul_hi_u32 s16, s7, s93
	s_mul_i32 s17, s16, s13
	s_sub_i32 s7, s7, s17
	s_ashr_i32 s6, s5, 31
	s_add_i32 s17, s16, 1
	s_sub_i32 s18, s7, s13
	s_cmp_ge_u32 s7, s13
	s_cselect_b32 s16, s17, s16
	s_cselect_b32 s7, s18, s7
	s_add_i32 s17, s16, 1
	s_cmp_ge_u32 s7, s13
	s_cselect_b32 s7, s17, s16
	s_xor_b32 s7, s7, s6
	s_sub_i32 s6, s7, s6
	s_lshl_b32 s7, s6, 3
	s_sub_i32 s16, 0x80, s7
	s_min_i32 s16, s16, 8
	s_abs_i32 s16, s16
	v_cvt_f32_u32_e32 v0, s16
	s_sub_i32 s17, 0, s16
	s_mul_i32 s6, s6, s13
	s_sub_i32 s5, s5, s6
	v_rcp_iflag_f32_e32 v0, v0
	s_ashr_i32 s6, s5, 31
	s_abs_i32 s5, s5
	v_mul_f32_e32 v0, 0x4f7ffffe, v0
	v_cvt_u32_f32_e32 v0, v0
	s_nop 0
	v_readfirstlane_b32 s18, v0
	s_mul_i32 s17, s17, s18
	s_mul_hi_u32 s17, s18, s17
	s_add_i32 s18, s18, s17
	s_mul_hi_u32 s17, s5, s18
	s_mul_i32 s17, s17, s16
	s_sub_i32 s5, s5, s17
	s_sub_i32 s17, s5, s16
	s_cmp_ge_u32 s5, s16
	s_cselect_b32 s5, s17, s5
	s_sub_i32 s17, s5, s16
	s_cmp_ge_u32 s5, s16
	s_cselect_b32 s5, s17, s5
	s_xor_b32 s5, s5, s6
	s_sub_i32 s5, s5, s6
	s_add_i32 s5, s5, s7
	s_add_i32 s6, s2, 1
	s_mov_b32 m0, s6
	s_nop 0
	v_writelane_b32 v31, s5, m0
	s_branch .LBB0_557

.LBB0_563:
	v_add_u32_e32 v8, s19, v166
	v_mov_b32_e32 v0, s95
	v_cmp_gt_i32_e64 s[2:3], s18, v8
	s_and_saveexec_b64 s[4:5], s[2:3]
	s_cbranch_execz .LBB0_567
	v_ashrrev_i32_e32 v0, 8, v8
	s_mov_b64 s[0:1], exec
	v_readfirstlane_b32 vcc_lo, v0
	s_nop 3
	v_readlane_b32 vcc_lo, v31, vcc_lo
	s_nop 1
	v_mov_b32_e32 v6, vcc_lo

.LBB0_567:
	s_or_b64 exec, exec, s[4:5]
	v_add_u32_e32 v2, 0x200, v8
	v_mov_b32_e32 v3, s95
	v_cmp_gt_i32_e64 s[4:5], s18, v2
	s_and_saveexec_b64 s[6:7], s[4:5]
	s_cbranch_execz .LBB0_571
	v_ashrrev_i32_e32 v7, 8, v2
	s_mov_b64 s[0:1], exec
	v_readfirstlane_b32 vcc_lo, v7
	s_nop 3
	v_readlane_b32 vcc_lo, v31, vcc_lo
	s_nop 1
	v_mov_b32_e32 v6, vcc_lo

.LBB0_571:
	s_or_b64 exec, exec, s[6:7]
	v_add_u32_e32 v7, 0x400, v8
	v_mov_b32_e32 v2, s95
	v_cmp_gt_i32_e64 s[0:1], s18, v7
	s_and_saveexec_b64 s[16:17], s[0:1]
	s_cbranch_execz .LBB0_577
	v_ashrrev_i32_e32 v2, 8, v7
	s_mov_b64 s[6:7], exec
	v_readfirstlane_b32 vcc_lo, v2
	s_nop 3
	v_readlane_b32 vcc_lo, v31, vcc_lo
	s_nop 1
	v_mov_b32_e32 v6, vcc_lo

.LBB0_581:
	s_nop 0
	s_nop 0
	s_nop 0
	s_nop 0
	s_nop 0
	s_nop 0
	s_nop 0
	s_nop 0
	s_nop 0
	s_nop 0
	s_nop 0
	s_nop 0
	s_nop 0
	s_nop 0
	s_nop 0
	s_nop 0
	s_nop 0
	s_cmp_lt_i32 s80, s94
	s_cselect_b64 s[2:3], -1, 0
	s_cmp_ge_i32 s80, s94
	v_readfirstlane_b32 s18, v166
	s_waitcnt vmcnt(0) lgkmcnt(0)
	s_barrier
	s_cbranch_scc1 .LBB0_583
	s_lshr_b32 s0, s81, 29
	s_add_i32 s0, s80, s0
	s_ashr_i32 s1, s0, 3
	s_and_b32 s0, s0, -8
	s_sub_i32 s0, s80, s0
	s_cmp_lt_i32 s0, 0
	s_cselect_b32 s4, s92, s57
	s_mul_i32 s0, s4, s0
	s_add_i32 s0, s0, s1
	s_abs_i32 s4, s0
	s_mul_hi_u32 s5, s4, s93
	s_mul_i32 s6, s5, s13
	s_sub_i32 s4, s4, s6
	s_ashr_i32 s1, s0, 31
	s_add_i32 s6, s5, 1
	s_sub_i32 s7, s4, s13
	s_cmp_ge_u32 s4, s13
	s_cselect_b32 s5, s6, s5
	s_cselect_b32 s4, s7, s4
	s_add_i32 s6, s5, 1
	s_cmp_ge_u32 s4, s13
	s_cselect_b32 s4, s6, s5
	s_xor_b32 s4, s4, s1
	s_sub_i32 s1, s4, s1
	s_lshl_b32 s4, s1, 3
	s_sub_i32 s5, 0x80, s4
	s_min_i32 s5, s5, 8
	s_abs_i32 s6, s5
	v_cvt_f32_u32_e32 v0, s6
	s_sub_i32 s16, 0, s6
	s_mul_i32 s1, s1, s13
	s_sub_i32 s0, s0, s1
	v_rcp_iflag_f32_e32 v0, v0
	s_abs_i32 s7, s0
	s_xor_b32 s1, s0, s5
	s_ashr_i32 s1, s1, 31
	v_mul_f32_e32 v0, 0x4f7ffffe, v0
	v_cvt_u32_f32_e32 v0, v0
	s_nop 0
	v_readfirstlane_b32 s17, v0
	s_mul_i32 s16, s16, s17
	s_mul_hi_u32 s16, s17, s16
	s_add_i32 s17, s17, s16
	s_mul_hi_u32 s16, s7, s17
	s_mul_i32 s17, s16, s6
	s_sub_i32 s7, s7, s17
	s_add_i32 s17, s16, 1
	s_sub_i32 s19, s7, s6
	s_cmp_ge_u32 s7, s6
	s_cselect_b32 s16, s17, s16
	s_cselect_b32 s7, s19, s7
	s_add_i32 s17, s16, 1
	s_cmp_ge_u32 s7, s6
	s_cselect_b32 s6, s17, s16
	s_xor_b32 s6, s6, s1
	s_sub_i32 s72, s6, s1
	s_mul_i32 s1, s72, s5
	s_sub_i32 s0, s0, s1
	s_add_i32 s0, s0, s4
.LBB0_583:
	s_andn2_b64 vcc, exec, s[2:3]
	s_cbranch_vccnz .LBB0_867
	v_bfe_i32 v3, v166, 27, 1
	v_lshlrev_b32_e32 v2, 4, v166
	v_lshrrev_b32_e32 v3, 22, v3
	v_add_u32_e32 v3, v2, v3
	v_and_b32_e32 v3, 0xfffffc00, v3
	v_sub_u32_e32 v3, v2, v3
	v_lshrrev_b32_e32 v4, 4, v3
	v_ashrrev_i32_e32 v0, 31, v166
	v_bitop3_b32 v3, v4, v3, 32 bitop3:0x6c
	v_lshrrev_b32_e32 v0, 26, v0
	v_ashrrev_i32_e32 v5, 31, v3
	v_add_u32_e32 v0, v166, v0
	v_lshrrev_b32_e32 v5, 26, v5
	v_ashrrev_i32_e32 v0, 6, v0
	v_add_u32_e32 v5, v3, v5
	v_lshlrev_b32_e32 v4, 3, v0
	v_ashrrev_i32_e32 v10, 6, v5
	v_and_b32_e32 v5, 0xc0, v5
	v_and_b32_e32 v4, -16, v4
	v_sub_u32_e32 v3, v3, v5
	v_add_u32_e32 v4, v10, v4
	v_ashrrev_i16_sdwa v3, v219, sext(v3) dst_sel:DWORD dst_unused:UNUSED_PAD src0_sel:DWORD src1_sel:BYTE_0
	v_lshlrev_b32_e32 v6, 5, v0
	v_bfe_i32 v11, v3, 0, 16
	v_lshlrev_b32_e32 v3, 1, v4
	v_lshrrev_b32_e32 v5, 2, v4
	v_and_b32_e32 v7, 3, v10
	s_mov_b32 s1, 0x1fffe0
	v_and_b32_e32 v6, 32, v6
	v_and_b32_e32 v3, 24, v3
	v_and_b32_e32 v5, 4, v5
	v_and_or_b32 v7, v4, s1, v7
	v_or3_b32 v3, v7, v5, v3
	v_add_lshl_u32 v5, v6, v11, 1
	v_add_u32_e32 v2, 0x2000, v2
	v_lshl_add_u32 v132, v3, 11, v5
	v_ashrrev_i32_e32 v3, 31, v2
	v_lshrrev_b32_e32 v3, 22, v3
	v_add_u32_e32 v3, v2, v3
	v_ashrrev_i32_e32 v12, 10, v3
	v_mul_i32_i24_e32 v3, 0x400, v12
	v_sub_u32_e32 v2, v2, v3
	v_lshrrev_b32_e32 v3, 4, v2
	v_bitop3_b32 v2, v3, v2, 32 bitop3:0x6c
	v_lshl_add_u32 v130, v4, 11, v5
	v_ashrrev_i32_e32 v4, 31, v2
	v_lshrrev_b32_e32 v4, 26, v4
	v_lshlrev_b32_e32 v3, 3, v12
	v_add_u32_e32 v4, v2, v4
	v_and_b32_e32 v3, -16, v3
	v_ashrrev_i32_e32 v13, 6, v4
	v_writelane_b32 v254, s78, 52
	v_add_u32_e32 v3, v13, v3
	v_and_b32_e32 v6, 3, v13
	v_writelane_b32 v254, s64, 48
	v_and_b32_e32 v4, 0xc0, v4
	v_and_or_b32 v6, v3, s1, v6
	s_ashr_i32 s3, s18, 6
	s_ashr_i32 s1, s0, 31
	s_ashr_i32 s73, s72, 31
	s_ashr_i32 s2, s18, 8
	v_sub_u32_e32 v2, v2, v4
	s_lshl_b32 s66, s3, 10
	s_lshl_b64 s[6:7], s[0:1], 19
	s_lshl_b64 s[4:5], s[72:73], 19
	v_readlane_b32 s10, v254, 39
	v_ashrrev_i16_sdwa v2, v219, sext(v2) dst_sel:DWORD dst_unused:UNUSED_PAD src0_sel:DWORD src1_sel:BYTE_0
	v_readlane_b32 s11, v254, 40
	s_add_u32 s4, s10, s4
	v_lshlrev_b32_e32 v5, 5, v12
	v_bfe_i32 v14, v2, 0, 16
	v_lshlrev_b32_e32 v2, 1, v3
	v_lshrrev_b32_e32 v4, 2, v3
	s_addc_u32 s5, s11, s5
	s_add_i32 s67, s66, 0
	v_and_b32_e32 v5, 32, v5
	v_and_b32_e32 v2, 24, v2
	v_and_b32_e32 v4, 4, v4
	s_add_i32 m0, s67, 0x10000
	v_or3_b32 v2, v6, v4, v2
	v_add_lshl_u32 v4, v5, v14, 1
	global_load_lds_dwordx4 v132, s[4:5]
	s_add_i32 m0, s67, 0x12000
	v_lshl_add_u32 v136, v2, 11, v4
	s_add_u32 s16, s4, 0x40000
	global_load_lds_dwordx4 v136, s[4:5]
	s_addc_u32 s17, s5, 0
	s_add_i32 m0, s67, 0x14000
	v_readlane_b32 s10, v254, 21
	global_load_lds_dwordx4 v132, s[16:17]
	s_add_i32 m0, s67, 0x16000
	v_readlane_b32 s11, v254, 22
	s_add_u32 s24, s10, s6
	s_addc_u32 s25, s11, s7
	s_add_i32 s73, s67, 0x2000
	global_load_lds_dwordx4 v136, s[16:17]
	s_mov_b32 m0, s67
	s_add_u32 s6, s24, 0x40000
	v_lshl_add_u32 v134, v3, 11, v4
	global_load_lds_dwordx4 v130, s[24:25]
	s_mov_b32 m0, s73
	s_addc_u32 s7, s25, 0
	s_add_i32 s20, s67, 0x4000
	global_load_lds_dwordx4 v134, s[24:25]
	s_mov_b32 m0, s20
	s_add_i32 s21, s67, 0x6000
	global_load_lds_dwordx4 v130, s[6:7]
	s_mov_b32 m0, s21
	s_cmp_eq_u32 s2, 1
	global_load_lds_dwordx4 v134, s[6:7]
	s_cselect_b64 s[6:7], -1, 0
	v_mov_b32_e32 v133, v1
	v_mov_b32_e32 v137, v1
	v_mov_b32_e32 v131, v1
	v_mov_b32_e32 v135, v1
	v_writelane_b32 v254, s6, 50
	v_lshl_add_u64 v[6:7], s[4:5], 0, v[132:133]
	v_lshl_add_u64 v[4:5], s[4:5], 0, v[136:137]
	v_lshl_add_u64 v[2:3], s[24:25], 0, v[130:131]
	v_writelane_b32 v254, s7, 51
	v_lshl_add_u64 v[8:9], s[24:25], 0, v[134:135]
	s_mov_b32 s101, s2
	s_add_u32 s6, s58, 0x28100000
	s_addc_u32 s7, s59, 0
	v_and_b32_e32 v167, 15, v166
	s_lshl_b32 s1, s2, 6
	v_lshrrev_b32_e32 v15, 1, v166
	v_writelane_b32 v254, s6, 42
	v_or_b32_e32 v188, s1, v167
	v_and_b32_e32 v15, 24, v15
	v_writelane_b32 v254, s7, 43
	v_lshlrev_b32_e32 v16, 1, v15
	v_lshlrev_b32_e32 v17, 2, v188
	v_writelane_b32 v254, s1, 41
	v_lshl_or_b32 v16, v167, 6, v16
	s_lshl_b32 s1, s2, 13
	v_and_b32_e32 v18, 32, v17
	v_bitop3_b32 v18, v16, s1, v18 bitop3:0xde
	s_lshl_b32 s1, s3, 5
	s_and_b32 s1, s1, 0x60
	s_lshl_b32 s2, s1, 7
	s_add_u32 s16, s58, s8
	v_lshlrev_b32_e32 v19, 2, v166
	s_addc_u32 s17, s59, s9
	s_add_i32 m0, s67, 0x18000
	v_lshl_add_u64 v[6:7], v[6:7], 0, s[22:23]
	v_and_b32_e32 v19, 32, v19
	global_load_lds_dwordx4 v[6:7], off
	v_lshl_add_u64 v[4:5], v[4:5], 0, s[22:23]
	s_add_i32 m0, s67, 0x1a000
	s_add_i32 s6, s67, 0x8000
	s_add_i32 s7, s67, 0xa000
	v_bitop3_b32 v189, s2, v16, v19 bitop3:0xf6
	global_load_lds_dwordx4 v[4:5], off
	v_lshl_add_u64 v[2:3], v[2:3], 0, s[22:23]
	s_mov_b32 m0, s6
	s_nop 0
	s_add_u32 s2, s4, 0x40080
	global_load_lds_dwordx4 v[2:3], off
	v_lshl_add_u64 v[2:3], v[8:9], 0, s[22:23]
	s_mov_b32 m0, s7
	s_addc_u32 s3, s5, 0
	global_load_lds_dwordx4 v[2:3], off
	s_add_i32 m0, s67, 0x1c000
	v_lshl_add_u64 v[2:3], s[2:3], 0, v[132:133]
	global_load_lds_dwordx4 v[2:3], off
	v_lshl_add_u64 v[2:3], s[2:3], 0, v[136:137]
	s_add_i32 m0, s67, 0x1e000
	s_nop 0
	global_load_lds_dwordx4 v[2:3], off
	s_cmp_lg_u32 s101, 1
	s_cbranch_scc1 .LBB0_586
	s_barrier

.Lip_skipB2:
	s_barrier
	s_add_i32 s24, s38, s66
	v_lshl_add_u64 v[186:187], v[186:187], 0, s[22:23]
	s_mov_b32 m0, s24
	ds_read_b128 v[194:197], v193 offset:49152
	ds_read_b128 v[198:201], v193 offset:50176
	ds_read_b128 v[206:209], v193 offset:51200
	ds_read_b128 v[210:213], v193 offset:52224
	ds_read_b128 v[214:217], v193 offset:53248
	ds_read_b128 v[238:241], v193 offset:54272
	ds_read_b128 v[242:245], v193 offset:55296
	ds_read_b128 v[246:249], v193 offset:56320
	global_load_lds_dwordx4 v[186:187], off
	s_add_i32 m0, s24, 0x2000
	s_add_u32 s8, s8, 0x40080
	v_lshl_add_u64 v[186:187], v[202:203], 0, s[22:23]
	s_addc_u32 s9, s9, 0
	s_add_i32 s24, s39, s66
	global_load_lds_dwordx4 v[186:187], off
	v_lshl_add_u64 v[186:187], s[8:9], 0, v[132:133]
	s_mov_b32 m0, s24
	s_nop 0
	global_load_lds_dwordx4 v[186:187], off
	v_lshl_add_u64 v[186:187], s[8:9], 0, v[136:137]
	s_add_i32 m0, s24, 0x2000
	s_nop 0
	global_load_lds_dwordx4 v[186:187], off
	v_lshl_add_u64 v[186:187], v[220:221], 0, s[22:23]
	s_mov_b32 m0, s6
	s_nop 0
	s_nop 0
	global_load_lds_dwordx4 v[186:187], off
	v_lshl_add_u64 v[186:187], v[250:251], 0, s[22:23]
	s_mov_b32 m0, s7
	s_nop 0
	global_load_lds_dwordx4 v[186:187], off
	s_waitcnt vmcnt(8)
	s_waitcnt lgkmcnt(0)
	s_barrier
	s_waitcnt lgkmcnt(0)
	s_bitcmp1_b32 s101, 0
	s_cbranch_scc1 .Lip_skipA3
	v_mfma_f32_16x16x32_bf16 v[62:65], v[142:145], v[194:197], v[62:65]
	v_mfma_f32_16x16x32_bf16 v[58:61], v[150:153], v[194:197], v[58:61]
	v_mfma_f32_16x16x32_bf16 v[46:49], v[142:145], v[206:209], v[46:49]
	v_mfma_f32_16x16x32_bf16 v[42:45], v[150:153], v[206:209], v[42:45]
	v_mfma_f32_16x16x32_bf16 v[30:33], v[142:145], v[214:217], v[30:33]
	v_mfma_f32_16x16x32_bf16 v[26:29], v[150:153], v[214:217], v[26:29]
	v_mfma_f32_16x16x32_bf16 v[14:17], v[142:145], v[242:245], v[14:17]
	v_mfma_f32_16x16x32_bf16 v[10:13], v[150:153], v[242:245], v[10:13]
	v_mfma_f32_16x16x32_bf16 v[62:65], v[146:149], v[198:201], v[62:65]
	v_mfma_f32_16x16x32_bf16 v[58:61], v[154:157], v[198:201], v[58:61]
	v_mfma_f32_16x16x32_bf16 v[46:49], v[146:149], v[210:213], v[46:49]
	v_mfma_f32_16x16x32_bf16 v[42:45], v[154:157], v[210:213], v[42:45]
	v_mfma_f32_16x16x32_bf16 v[30:33], v[146:149], v[238:241], v[30:33]
	v_mfma_f32_16x16x32_bf16 v[26:29], v[154:157], v[238:241], v[26:29]
	v_mfma_f32_16x16x32_bf16 v[14:17], v[146:149], v[246:249], v[14:17]
	v_mfma_f32_16x16x32_bf16 v[10:13], v[154:157], v[246:249], v[10:13]

.LBB0_592:
	s_add_u32 s8, s4, 0xfffc0080
	s_addc_u32 s9, s5, -1
	s_add_i32 s38, 0, 0x10000
	s_cmp_eq_u32 s35, 12
	s_cselect_b32 s25, s1, s9
	s_cselect_b32 s24, s26, s8
	v_add_u32_e32 v0, s38, v189
	s_cselect_b32 s9, s27, s34
	s_cselect_b32 s8, s28, s29
	s_add_i32 s64, 0, 0x14000
	s_waitcnt lgkmcnt(0)
	ds_read_b128 v[142:145], v0
	ds_read_b128 v[146:149], v0 offset:1024
	ds_read_b128 v[150:153], v0 offset:2048
	ds_read_b128 v[154:157], v0 offset:3072
	v_add_u32_e32 v0, s64, v189
	ds_read_b128 v[170:173], v0
	ds_read_b128 v[174:177], v0 offset:1024
	ds_read_b128 v[178:181], v0 offset:2048
	ds_read_b128 v[182:185], v0 offset:3072
	v_lshl_add_u64 v[186:187], s[4:5], 0, v[140:141]
	s_add_i32 m0, s67, 0xc000
	ds_read_b128 v[194:197], v193
	ds_read_b128 v[198:201], v193 offset:1024
	ds_read_b128 v[206:209], v193 offset:2048
	ds_read_b128 v[210:213], v193 offset:3072
	ds_read_b128 v[214:217], v193 offset:4096
	ds_read_b128 v[238:241], v193 offset:5120
	ds_read_b128 v[242:245], v193 offset:6144
	ds_read_b128 v[246:249], v193 offset:7168
	global_load_lds_dwordx4 v[186:187], off
	v_lshl_add_u64 v[186:187], s[4:5], 0, v[138:139]
	s_add_i32 m0, s67, 0xe000
	s_nop 0
	global_load_lds_dwordx4 v[186:187], off
	s_waitcnt vmcnt(8)
	s_waitcnt lgkmcnt(0)
	s_barrier
	s_waitcnt lgkmcnt(0)
	v_mfma_f32_16x16x32_bf16 v[126:129], v[142:145], v[194:197], v[126:129]
	v_mfma_f32_16x16x32_bf16 v[122:125], v[150:153], v[194:197], v[122:125]
	v_mfma_f32_16x16x32_bf16 v[110:113], v[142:145], v[206:209], v[110:113]
	v_mfma_f32_16x16x32_bf16 v[106:109], v[150:153], v[206:209], v[106:109]
	v_mfma_f32_16x16x32_bf16 v[94:97], v[142:145], v[214:217], v[94:97]
	v_mfma_f32_16x16x32_bf16 v[90:93], v[150:153], v[214:217], v[90:93]
	v_mfma_f32_16x16x32_bf16 v[78:81], v[142:145], v[242:245], v[78:81]
	v_mfma_f32_16x16x32_bf16 v[74:77], v[150:153], v[242:245], v[74:77]
	v_mfma_f32_16x16x32_bf16 v[126:129], v[146:149], v[198:201], v[126:129]
	v_mfma_f32_16x16x32_bf16 v[122:125], v[154:157], v[198:201], v[122:125]
	v_mfma_f32_16x16x32_bf16 v[110:113], v[146:149], v[210:213], v[110:113]
	v_mfma_f32_16x16x32_bf16 v[106:109], v[154:157], v[210:213], v[106:109]
	v_mfma_f32_16x16x32_bf16 v[94:97], v[146:149], v[238:241], v[94:97]
	v_mfma_f32_16x16x32_bf16 v[90:93], v[154:157], v[238:241], v[90:93]
	v_mfma_f32_16x16x32_bf16 v[78:81], v[146:149], v[246:249], v[78:81]
	v_mfma_f32_16x16x32_bf16 v[74:77], v[154:157], v[246:249], v[74:77]
	v_mfma_f32_16x16x32_bf16 v[118:121], v[170:173], v[194:197], v[118:121]
	v_mfma_f32_16x16x32_bf16 v[114:117], v[178:181], v[194:197], v[114:117]
	v_mfma_f32_16x16x32_bf16 v[102:105], v[170:173], v[206:209], v[102:105]
	v_mfma_f32_16x16x32_bf16 v[98:101], v[178:181], v[206:209], v[98:101]
	v_mfma_f32_16x16x32_bf16 v[86:89], v[170:173], v[214:217], v[86:89]
	v_mfma_f32_16x16x32_bf16 v[82:85], v[178:181], v[214:217], v[82:85]
	v_mfma_f32_16x16x32_bf16 v[70:73], v[170:173], v[242:245], v[70:73]
	v_mfma_f32_16x16x32_bf16 v[66:69], v[178:181], v[242:245], v[66:69]
	v_mfma_f32_16x16x32_bf16 v[118:121], v[174:177], v[198:201], v[118:121]
	v_mfma_f32_16x16x32_bf16 v[114:117], v[182:185], v[198:201], v[114:117]
	v_mfma_f32_16x16x32_bf16 v[102:105], v[174:177], v[210:213], v[102:105]
	v_mfma_f32_16x16x32_bf16 v[98:101], v[182:185], v[210:213], v[98:101]
	v_mfma_f32_16x16x32_bf16 v[86:89], v[174:177], v[238:241], v[86:89]
	v_mfma_f32_16x16x32_bf16 v[82:85], v[182:185], v[238:241], v[82:85]
	v_mfma_f32_16x16x32_bf16 v[70:73], v[174:177], v[246:249], v[70:73]
	v_mfma_f32_16x16x32_bf16 v[66:69], v[182:185], v[246:249], v[66:69]
	s_barrier
	s_add_i32 s38, s38, s66
	v_lshl_add_u64 v[186:187], s[8:9], 0, v[132:133]
	s_mov_b32 m0, s38
	ds_read_b128 v[194:197], v193 offset:16384
	ds_read_b128 v[198:201], v193 offset:17408
	ds_read_b128 v[206:209], v193 offset:18432
	ds_read_b128 v[210:213], v193 offset:19456
	ds_read_b128 v[214:217], v193 offset:20480
	ds_read_b128 v[238:241], v193 offset:21504
	ds_read_b128 v[242:245], v193 offset:22528
	ds_read_b128 v[246:249], v193 offset:23552
	global_load_lds_dwordx4 v[186:187], off
	s_add_i32 m0, s38, 0x2000
	s_add_u32 s38, s8, 0x40000
	v_lshl_add_u64 v[202:203], s[8:9], 0, v[136:137]
	s_addc_u32 s39, s9, 0
	s_add_i32 s64, s64, s66
	global_load_lds_dwordx4 v[202:203], off
	v_lshl_add_u64 v[220:221], s[38:39], 0, v[132:133]
	s_mov_b32 m0, s64
	v_lshl_add_u64 v[250:251], s[24:25], 0, v[134:135]
	global_load_lds_dwordx4 v[220:221], off
	v_lshl_add_u64 v[220:221], s[38:39], 0, v[136:137]
	s_add_i32 m0, s64, 0x2000
	s_nop 0
	global_load_lds_dwordx4 v[220:221], off
	v_lshl_add_u64 v[220:221], s[24:25], 0, v[130:131]
	s_mov_b32 m0, s67
	s_nop 0
	global_load_lds_dwordx4 v[220:221], off
	s_mov_b32 m0, s73
	s_nop 0
	global_load_lds_dwordx4 v[250:251], off
	s_waitcnt vmcnt(8)
	s_waitcnt lgkmcnt(0)
	s_barrier
	s_waitcnt lgkmcnt(0)
	v_mfma_f32_16x16x32_bf16 v[62:65], v[142:145], v[194:197], v[62:65]
	v_mfma_f32_16x16x32_bf16 v[58:61], v[150:153], v[194:197], v[58:61]
	v_mfma_f32_16x16x32_bf16 v[46:49], v[142:145], v[206:209], v[46:49]
	v_mfma_f32_16x16x32_bf16 v[42:45], v[150:153], v[206:209], v[42:45]
	v_mfma_f32_16x16x32_bf16 v[30:33], v[142:145], v[214:217], v[30:33]
	v_mfma_f32_16x16x32_bf16 v[26:29], v[150:153], v[214:217], v[26:29]
	v_mfma_f32_16x16x32_bf16 v[14:17], v[142:145], v[242:245], v[14:17]
	v_mfma_f32_16x16x32_bf16 v[10:13], v[150:153], v[242:245], v[10:13]
	v_mfma_f32_16x16x32_bf16 v[62:65], v[146:149], v[198:201], v[62:65]
	v_mfma_f32_16x16x32_bf16 v[58:61], v[154:157], v[198:201], v[58:61]
	v_mfma_f32_16x16x32_bf16 v[46:49], v[146:149], v[210:213], v[46:49]
	v_mfma_f32_16x16x32_bf16 v[42:45], v[154:157], v[210:213], v[42:45]
	v_mfma_f32_16x16x32_bf16 v[30:33], v[146:149], v[238:241], v[30:33]
	v_mfma_f32_16x16x32_bf16 v[26:29], v[154:157], v[238:241], v[26:29]
	v_mfma_f32_16x16x32_bf16 v[14:17], v[146:149], v[246:249], v[14:17]
	v_mfma_f32_16x16x32_bf16 v[10:13], v[154:157], v[246:249], v[10:13]
	v_mfma_f32_16x16x32_bf16 v[54:57], v[170:173], v[194:197], v[54:57]
	v_mfma_f32_16x16x32_bf16 v[50:53], v[178:181], v[194:197], v[50:53]
	v_mfma_f32_16x16x32_bf16 v[38:41], v[170:173], v[206:209], v[38:41]
	v_mfma_f32_16x16x32_bf16 v[34:37], v[178:181], v[206:209], v[34:37]
	v_mfma_f32_16x16x32_bf16 v[22:25], v[170:173], v[214:217], v[22:25]
	v_mfma_f32_16x16x32_bf16 v[18:21], v[178:181], v[214:217], v[18:21]
	v_mfma_f32_16x16x32_bf16 v[6:9], v[170:173], v[242:245], v[6:9]
	v_mfma_f32_16x16x32_bf16 v[2:5], v[178:181], v[242:245], v[2:5]
	v_mfma_f32_16x16x32_bf16 v[54:57], v[174:177], v[198:201], v[54:57]
	v_mfma_f32_16x16x32_bf16 v[50:53], v[182:185], v[198:201], v[50:53]
	v_mfma_f32_16x16x32_bf16 v[38:41], v[174:177], v[210:213], v[38:41]
	v_mfma_f32_16x16x32_bf16 v[34:37], v[182:185], v[210:213], v[34:37]
	v_mfma_f32_16x16x32_bf16 v[22:25], v[174:177], v[238:241], v[22:25]
	v_mfma_f32_16x16x32_bf16 v[18:21], v[182:185], v[238:241], v[18:21]
	v_mfma_f32_16x16x32_bf16 v[6:9], v[174:177], v[246:249], v[6:9]
	v_mfma_f32_16x16x32_bf16 v[2:5], v[182:185], v[246:249], v[2:5]
	s_barrier
	s_add_i32 s38, 0, 0x18000
	v_add_u32_e32 v0, s38, v189
	s_add_i32 s39, 0, 0x1c000
	ds_read_b128 v[142:145], v0
	ds_read_b128 v[146:149], v0 offset:1024
	ds_read_b128 v[150:153], v0 offset:2048
	ds_read_b128 v[154:157], v0 offset:3072
	v_add_u32_e32 v0, s39, v189
	ds_read_b128 v[170:173], v0
	ds_read_b128 v[174:177], v0 offset:1024
	ds_read_b128 v[178:181], v0 offset:2048
	ds_read_b128 v[182:185], v0 offset:3072
	s_add_u32 s24, s24, 0x40000
	s_addc_u32 s25, s25, 0
	s_mov_b32 m0, s20
	v_lshl_add_u64 v[226:227], s[24:25], 0, v[130:131]
	ds_read_b128 v[194:197], v193 offset:32768
	ds_read_b128 v[198:201], v193 offset:33792
	ds_read_b128 v[206:209], v193 offset:34816
	ds_read_b128 v[210:213], v193 offset:35840
	ds_read_b128 v[214:217], v193 offset:36864
	ds_read_b128 v[238:241], v193 offset:37888
	ds_read_b128 v[242:245], v193 offset:38912
	ds_read_b128 v[246:249], v193 offset:39936
	global_load_lds_dwordx4 v[226:227], off
	v_lshl_add_u64 v[226:227], s[24:25], 0, v[134:135]
	s_mov_b32 m0, s21
	s_nop 0
	global_load_lds_dwordx4 v[226:227], off
	s_waitcnt vmcnt(8)
	s_waitcnt lgkmcnt(0)
	s_barrier
	s_waitcnt lgkmcnt(0)
	v_mfma_f32_16x16x32_bf16 v[126:129], v[142:145], v[194:197], v[126:129]
	v_mfma_f32_16x16x32_bf16 v[122:125], v[150:153], v[194:197], v[122:125]
	v_mfma_f32_16x16x32_bf16 v[110:113], v[142:145], v[206:209], v[110:113]
	v_mfma_f32_16x16x32_bf16 v[106:109], v[150:153], v[206:209], v[106:109]
	v_mfma_f32_16x16x32_bf16 v[94:97], v[142:145], v[214:217], v[94:97]
	v_mfma_f32_16x16x32_bf16 v[90:93], v[150:153], v[214:217], v[90:93]
	v_mfma_f32_16x16x32_bf16 v[78:81], v[142:145], v[242:245], v[78:81]
	v_mfma_f32_16x16x32_bf16 v[74:77], v[150:153], v[242:245], v[74:77]
	v_mfma_f32_16x16x32_bf16 v[126:129], v[146:149], v[198:201], v[126:129]
	v_mfma_f32_16x16x32_bf16 v[122:125], v[154:157], v[198:201], v[122:125]
	v_mfma_f32_16x16x32_bf16 v[110:113], v[146:149], v[210:213], v[110:113]
	v_mfma_f32_16x16x32_bf16 v[106:109], v[154:157], v[210:213], v[106:109]
	v_mfma_f32_16x16x32_bf16 v[94:97], v[146:149], v[238:241], v[94:97]
	v_mfma_f32_16x16x32_bf16 v[90:93], v[154:157], v[238:241], v[90:93]
	v_mfma_f32_16x16x32_bf16 v[78:81], v[146:149], v[246:249], v[78:81]
	v_mfma_f32_16x16x32_bf16 v[74:77], v[154:157], v[246:249], v[74:77]
	v_mfma_f32_16x16x32_bf16 v[118:121], v[170:173], v[194:197], v[118:121]
	v_mfma_f32_16x16x32_bf16 v[114:117], v[178:181], v[194:197], v[114:117]
	v_mfma_f32_16x16x32_bf16 v[102:105], v[170:173], v[206:209], v[102:105]
	v_mfma_f32_16x16x32_bf16 v[98:101], v[178:181], v[206:209], v[98:101]
	v_mfma_f32_16x16x32_bf16 v[86:89], v[170:173], v[214:217], v[86:89]
	v_mfma_f32_16x16x32_bf16 v[82:85], v[178:181], v[214:217], v[82:85]
	v_mfma_f32_16x16x32_bf16 v[70:73], v[170:173], v[242:245], v[70:73]
	v_mfma_f32_16x16x32_bf16 v[66:69], v[178:181], v[242:245], v[66:69]
	v_mfma_f32_16x16x32_bf16 v[118:121], v[174:177], v[198:201], v[118:121]
	v_mfma_f32_16x16x32_bf16 v[114:117], v[182:185], v[198:201], v[114:117]
	v_mfma_f32_16x16x32_bf16 v[102:105], v[174:177], v[210:213], v[102:105]
	v_mfma_f32_16x16x32_bf16 v[98:101], v[182:185], v[210:213], v[98:101]
	v_mfma_f32_16x16x32_bf16 v[86:89], v[174:177], v[238:241], v[86:89]
	v_mfma_f32_16x16x32_bf16 v[82:85], v[182:185], v[238:241], v[82:85]
	v_mfma_f32_16x16x32_bf16 v[70:73], v[174:177], v[246:249], v[70:73]
	v_mfma_f32_16x16x32_bf16 v[66:69], v[182:185], v[246:249], v[66:69]
	s_barrier
	s_add_i32 s24, s38, s66
	v_lshl_add_u64 v[186:187], v[186:187], 0, s[22:23]
	s_mov_b32 m0, s24
	ds_read_b128 v[194:197], v193 offset:49152
	ds_read_b128 v[198:201], v193 offset:50176
	ds_read_b128 v[206:209], v193 offset:51200
	ds_read_b128 v[210:213], v193 offset:52224
	ds_read_b128 v[214:217], v193 offset:53248
	ds_read_b128 v[238:241], v193 offset:54272
	ds_read_b128 v[242:245], v193 offset:55296
	ds_read_b128 v[246:249], v193 offset:56320
	global_load_lds_dwordx4 v[186:187], off
	s_add_i32 m0, s24, 0x2000
	s_add_u32 s8, s8, 0x40080
	v_lshl_add_u64 v[186:187], v[202:203], 0, s[22:23]
	s_addc_u32 s9, s9, 0
	s_add_i32 s24, s39, s66
	global_load_lds_dwordx4 v[186:187], off
	v_lshl_add_u64 v[186:187], s[8:9], 0, v[132:133]
	s_mov_b32 m0, s24
	s_nop 0
	global_load_lds_dwordx4 v[186:187], off
	v_lshl_add_u64 v[186:187], s[8:9], 0, v[136:137]
	s_add_i32 m0, s24, 0x2000
	s_nop 0
	global_load_lds_dwordx4 v[186:187], off
	v_lshl_add_u64 v[186:187], v[220:221], 0, s[22:23]
	s_mov_b32 m0, s6
	s_nop 0
	s_nop 0
	global_load_lds_dwordx4 v[186:187], off
	v_lshl_add_u64 v[186:187], v[250:251], 0, s[22:23]
	s_mov_b32 m0, s7
	s_nop 0
	global_load_lds_dwordx4 v[186:187], off
	s_waitcnt vmcnt(8)
	s_waitcnt lgkmcnt(0)
	s_barrier
	s_waitcnt lgkmcnt(0)
	v_mfma_f32_16x16x32_bf16 v[62:65], v[142:145], v[194:197], v[62:65]
	v_mfma_f32_16x16x32_bf16 v[58:61], v[150:153], v[194:197], v[58:61]
	v_mfma_f32_16x16x32_bf16 v[46:49], v[142:145], v[206:209], v[46:49]
	v_mfma_f32_16x16x32_bf16 v[42:45], v[150:153], v[206:209], v[42:45]
	v_mfma_f32_16x16x32_bf16 v[30:33], v[142:145], v[214:217], v[30:33]
	v_mfma_f32_16x16x32_bf16 v[26:29], v[150:153], v[214:217], v[26:29]
	v_mfma_f32_16x16x32_bf16 v[14:17], v[142:145], v[242:245], v[14:17]
	v_mfma_f32_16x16x32_bf16 v[10:13], v[150:153], v[242:245], v[10:13]
	v_mfma_f32_16x16x32_bf16 v[62:65], v[146:149], v[198:201], v[62:65]
	v_mfma_f32_16x16x32_bf16 v[58:61], v[154:157], v[198:201], v[58:61]
	v_mfma_f32_16x16x32_bf16 v[46:49], v[146:149], v[210:213], v[46:49]
	v_mfma_f32_16x16x32_bf16 v[42:45], v[154:157], v[210:213], v[42:45]
	v_mfma_f32_16x16x32_bf16 v[30:33], v[146:149], v[238:241], v[30:33]
	v_mfma_f32_16x16x32_bf16 v[26:29], v[154:157], v[238:241], v[26:29]
	v_mfma_f32_16x16x32_bf16 v[14:17], v[146:149], v[246:249], v[14:17]
	v_mfma_f32_16x16x32_bf16 v[10:13], v[154:157], v[246:249], v[10:13]
	v_mfma_f32_16x16x32_bf16 v[54:57], v[170:173], v[194:197], v[54:57]
	v_mfma_f32_16x16x32_bf16 v[50:53], v[178:181], v[194:197], v[50:53]
	v_mfma_f32_16x16x32_bf16 v[38:41], v[170:173], v[206:209], v[38:41]
	v_mfma_f32_16x16x32_bf16 v[34:37], v[178:181], v[206:209], v[34:37]
	v_mfma_f32_16x16x32_bf16 v[22:25], v[170:173], v[214:217], v[22:25]
	v_mfma_f32_16x16x32_bf16 v[18:21], v[178:181], v[214:217], v[18:21]
	v_mfma_f32_16x16x32_bf16 v[6:9], v[170:173], v[242:245], v[6:9]
	v_mfma_f32_16x16x32_bf16 v[2:5], v[178:181], v[242:245], v[2:5]
	v_mfma_f32_16x16x32_bf16 v[54:57], v[174:177], v[198:201], v[54:57]
	v_mfma_f32_16x16x32_bf16 v[50:53], v[182:185], v[198:201], v[50:53]
	v_mfma_f32_16x16x32_bf16 v[38:41], v[174:177], v[210:213], v[38:41]
	v_mfma_f32_16x16x32_bf16 v[34:37], v[182:185], v[210:213], v[34:37]
	v_mfma_f32_16x16x32_bf16 v[22:25], v[174:177], v[238:241], v[22:25]
	v_mfma_f32_16x16x32_bf16 v[18:21], v[182:185], v[238:241], v[18:21]
	v_mfma_f32_16x16x32_bf16 v[6:9], v[174:177], v[246:249], v[6:9]
	v_mfma_f32_16x16x32_bf16 v[2:5], v[182:185], v[246:249], v[2:5]
	s_barrier
	s_add_i32 s35, s35, 2
	s_add_u32 s29, s29, 0x100
	s_addc_u32 s34, s34, 0
	s_add_u32 s4, s4, 0x100
	s_addc_u32 s5, s5, 0
	s_cmp_gt_u32 s35, 13
	s_cbranch_scc0 .LBB0_592

.LBB0_885:
	s_nop 0
	s_nop 0
	s_nop 0
	s_nop 0
	s_nop 0
	s_nop 0
	s_nop 0
	s_nop 0
	s_nop 0
	s_nop 0
	s_nop 0
	s_nop 0
	s_nop 0
	s_nop 0
	s_nop 0
	s_nop 0
	s_nop 0
	s_nop 0
	s_nop 0
	s_nop 0
	s_nop 0
	s_nop 0
	s_nop 0
	s_nop 0
	s_nop 0
	s_nop 0
	s_nop 0
	s_nop 0
	s_nop 0
	s_nop 0
	s_nop 0
	s_nop 0
	s_nop 0
	s_nop 0
	s_nop 0
	s_nop 0
	s_nop 0
	s_nop 0
	s_nop 0
	s_nop 0
	s_nop 0
	s_nop 0
	s_nop 0
	s_nop 0
	s_nop 0
	s_nop 0
	s_nop 0
	s_nop 0
	s_nop 0
	s_nop 0
	s_nop 0
	s_nop 0
	s_nop 0
	s_nop 0
	s_nop 0
	s_nop 0
	s_nop 0
	s_nop 0
	s_nop 0
	s_nop 0
	s_nop 0
	s_nop 0
	s_nop 0
	s_waitcnt vmcnt(8)
	s_barrier
	s_cmpk_lt_u32 s4, 0x100
	v_lshrrev_b32_e32 v3, 1, v14
	v_mul_lo_u32 v2, v16, s5
	s_mov_b32 s4, 0xb000
	v_mad_u64_u32 v[2:3], s[0:1], v3, s4, v[2:3]
	v_or_b32_e32 v2, v2, v15
	v_add_lshl_u32 v2, v2, v17, 1
	v_mov_b32_e32 v3, v1
	s_mov_b64 s[16:17], 0xb0080
	v_lshl_add_u64 v[136:137], v[2:3], 0, s[16:17]
	v_lshrrev_b32_e32 v3, 1, v10
	v_mul_lo_u32 v2, v12, s5
	v_mad_u64_u32 v[2:3], s[0:1], v3, s4, v[2:3]
	s_waitcnt vmcnt(6)
	v_or_b32_e32 v2, v2, v11
	v_lshlrev_b32_e32 v20, 3, v19
	v_add_lshl_u32 v2, v2, v13, 1
	v_mov_b32_e32 v3, v1
	s_mov_b32 s39, 0
	v_lshl_or_b32 v146, s57, 5, v20
	s_cselect_b64 s[12:13], -1, 0
	v_cmp_eq_u32_e64 s[2:3], 0, v19
	s_ashr_i32 s65, s63, 31
	s_ashr_i32 s66, s80, 31
	v_lshl_add_u64 v[138:139], v[2:3], 0, s[16:17]
	v_add_u32_e32 v147, 0, v22
	s_barrier
	s_branch .LBB0_889

.LBB0_928:
	v_cmp_gt_i64_e32 vcc, s[0:1], v[162:163]
	s_cbranch_vccnz .LBB0_927
	s_ashr_i32 s5, s0, 31
	s_lshr_b32 s5, s5, 29
	s_add_i32 s5, s0, s5
	s_ashr_i32 s6, s5, 3
	s_and_b32 s5, s5, -8
	s_sub_i32 s5, s0, s5
	s_cmp_lt_i32 s5, 0
	s_movk_i32 s7, 0x161
	s_cselect_b32 s7, s7, 0x160
	s_mul_i32 s5, s5, s7
	s_add_i32 s5, s5, s6
	s_mul_hi_i32 s6, s5, 0x2e8ba2e9
	s_lshr_b32 s7, s6, 31
	s_ashr_i32 s6, s6, 5
	s_add_i32 s6, s6, s7
	s_lshl_b32 s7, s6, 3
	s_sub_i32 s8, 0x80, s7
	s_min_i32 s8, s8, 8
	s_abs_i32 s8, s8
	v_cvt_f32_u32_e32 v0, s8
	s_sub_i32 s9, 0, s8
	s_mulk_i32 s6, 0xb0
	s_sub_i32 s5, s5, s6
	v_rcp_iflag_f32_e32 v0, v0
	s_ashr_i32 s6, s5, 31
	s_abs_i32 s5, s5
	v_mul_f32_e32 v0, 0x4f7ffffe, v0
	v_cvt_u32_f32_e32 v0, v0
	s_nop 0
	v_readfirstlane_b32 s10, v0
	s_mul_i32 s9, s9, s10
	s_mul_hi_u32 s9, s10, s9
	s_add_i32 s10, s10, s9
	s_mul_hi_u32 s9, s5, s10
	s_mul_i32 s9, s9, s8
	s_sub_i32 s5, s5, s9
	s_sub_i32 s9, s5, s8
	s_cmp_ge_u32 s5, s8
	s_cselect_b32 s5, s9, s5
	s_sub_i32 s9, s5, s8
	s_cmp_ge_u32 s5, s8
	s_cselect_b32 s5, s9, s5
	s_xor_b32 s5, s5, s6
	s_sub_i32 s5, s5, s6
	s_add_i32 s5, s7, s5
	s_add_i32 s6, s2, 1
	s_mov_b32 m0, s6
	s_nop 0
	v_writelane_b32 v31, s5, m0
	s_branch .LBB0_927

.LBB0_933:
	v_add_u32_e32 v8, s11, v166
	v_mov_b32_e32 v0, s95
	v_cmp_gt_i32_e64 s[2:3], s10, v8
	s_and_saveexec_b64 s[4:5], s[2:3]
	s_cbranch_execz .LBB0_937
	v_ashrrev_i32_e32 v0, 8, v8
	s_mov_b64 s[0:1], exec
	v_readfirstlane_b32 vcc_lo, v0
	s_nop 3
	v_readlane_b32 vcc_lo, v31, vcc_lo
	s_nop 1
	v_mov_b32_e32 v6, vcc_lo

.LBB0_937:
	s_or_b64 exec, exec, s[4:5]
	v_add_u32_e32 v2, 0x200, v8
	v_mov_b32_e32 v3, s95
	v_cmp_gt_i32_e64 s[0:1], s10, v2
	s_and_saveexec_b64 s[6:7], s[0:1]
	s_cbranch_execz .LBB0_941
	v_ashrrev_i32_e32 v7, 8, v2
	s_mov_b64 s[4:5], exec
	v_readfirstlane_b32 vcc_lo, v7
	s_nop 3
	v_readlane_b32 vcc_lo, v31, vcc_lo
	s_nop 1
	v_mov_b32_e32 v6, vcc_lo

.LBB0_941:
	s_or_b64 exec, exec, s[6:7]
	v_add_u32_e32 v7, 0x400, v8
	v_mov_b32_e32 v2, s95
	v_cmp_gt_i32_e64 s[4:5], s10, v7
	s_and_saveexec_b64 s[8:9], s[4:5]
	s_cbranch_execz .LBB0_947
	v_ashrrev_i32_e32 v2, 8, v7
	s_mov_b64 s[6:7], exec
	v_readfirstlane_b32 vcc_lo, v2
	s_nop 3
	v_readlane_b32 vcc_lo, v31, vcc_lo
	s_nop 1
	v_mov_b32_e32 v6, vcc_lo

.LBB0_951:
	s_nop 0
	s_nop 0
	s_nop 0
	s_nop 0
	s_nop 0
	s_nop 0
	s_nop 0
	s_nop 0
	s_nop 0
	s_nop 0
	s_nop 0
	s_nop 0
	s_nop 0
	s_nop 0
	s_nop 0
	s_nop 0
	s_nop 0
	s_nop 0
	s_nop 0
	s_nop 0
	s_nop 0
	s_nop 0
	s_nop 0
	s_nop 0
	s_nop 0
	s_nop 0
	s_nop 0
	s_nop 0
	s_nop 0
	s_nop 0
	s_nop 0
	s_nop 0
	s_nop 0
	s_nop 0
	s_nop 0
	s_nop 0
	s_nop 0
	s_nop 0
	s_nop 0
	s_nop 0
	s_nop 0
	s_nop 0
	s_nop 0
	s_nop 0
	s_nop 0
	s_nop 0
	s_nop 0
	s_nop 0
	s_nop 0
	s_nop 0
	s_cmpk_gt_i32 s80, 0xaff
	v_readfirstlane_b32 s3, v166
	s_waitcnt vmcnt(0) lgkmcnt(0)
	s_barrier
	s_cbranch_scc1 .LBB0_967
	v_lshlrev_b32_e32 v0, 4, v166
	v_add_u32_e32 v2, 0x2000, v0
	v_ashrrev_i32_e32 v3, 31, v2
	v_lshrrev_b32_e32 v3, 22, v3
	v_add_u32_e32 v3, v2, v3
	v_ashrrev_i32_e32 v10, 10, v3
	s_mov_b32 s0, s18
	s_ashr_i32 s5, s3, 6
	v_mul_i32_i24_e32 v3, 0x400, v10
	s_ashr_i32 s4, s3, 8
	s_lshl_b32 s18, s5, 10
	s_mov_b32 s8, s0
	s_and_b32 s0, s0, 1
	v_sub_u32_e32 v2, v2, v3
	s_add_u32 s1, s58, 0x1b800000
	v_lshrrev_b32_e32 v3, 4, v2
	s_addc_u32 s2, s59, 0
	v_bitop3_b32 v2, v3, v2, 32 bitop3:0x6c
	s_cmp_eq_u32 s0, 0
	v_readlane_b32 s6, v254, 21
	v_ashrrev_i32_e32 v3, 31, v2
	v_readlane_b32 s7, v254, 22
	s_cselect_b32 s29, s6, s1
	s_mul_i32 s1, s8, 0xb00000
	v_lshrrev_b32_e32 v3, 26, v3
	s_cselect_b32 s19, s7, s2
	s_mul_hi_u32 s0, s8, 0xb00000
	s_add_u32 s1, s58, s1
	v_add_u32_e32 v3, v2, v3
	v_lshlrev_b32_e32 v4, 3, v10
	s_addc_u32 s0, s59, s0
	v_ashrrev_i32_e32 v11, 6, v3
	v_and_b32_e32 v4, -16, v4
	s_add_u32 s30, s1, 0x100000
	v_add_u32_e32 v4, v11, v4
	s_addc_u32 s31, s0, 0
	v_and_b32_e32 v5, 3, v11
	s_mov_b32 s0, 0x1fffe0
	v_lshrrev_b32_e32 v6, 2, v4
	v_lshlrev_b32_e32 v7, 1, v4
	v_and_b32_e32 v3, 0xc0, v3
	v_and_or_b32 v5, v4, s0, v5
	v_and_b32_e32 v6, 4, v6
	v_and_b32_e32 v7, 24, v7
	v_sub_u32_e32 v2, v2, v3
	v_or3_b32 v5, v5, v6, v7
	v_lshlrev_b32_e32 v6, 5, v10
	v_ashrrev_i16_sdwa v2, v219, sext(v2) dst_sel:DWORD dst_unused:UNUSED_PAD src0_sel:DWORD src1_sel:BYTE_0
	v_and_b32_e32 v6, 32, v6
	v_bfe_i32 v12, v2, 0, 16
	v_add_lshl_u32 v2, v6, v12, 1
	v_lshl_add_u32 v130, v5, 11, v2
	v_lshl_add_u32 v132, v4, 11, v2
	v_bfe_i32 v2, v166, 27, 1
	v_lshrrev_b32_e32 v2, 22, v2
	v_add_u32_e32 v2, v0, v2
	v_and_b32_e32 v2, 0xfffffc00, v2
	v_sub_u32_e32 v0, v0, v2
	v_lshrrev_b32_e32 v2, 4, v0
	v_ashrrev_i32_e32 v3, 31, v166
	v_bitop3_b32 v0, v2, v0, 32 bitop3:0x6c
	v_lshrrev_b32_e32 v3, 26, v3
	v_ashrrev_i32_e32 v2, 31, v0
	v_add_u32_e32 v3, v166, v3
	v_lshrrev_b32_e32 v2, 26, v2
	v_ashrrev_i32_e32 v14, 6, v3
	v_add_u32_e32 v2, v0, v2
	v_lshlrev_b32_e32 v3, 3, v14
	v_ashrrev_i32_e32 v13, 6, v2
	v_and_b32_e32 v3, -16, v3
	v_add_u32_e32 v3, v13, v3
	v_and_b32_e32 v4, 3, v13
	v_and_or_b32 v4, v3, s0, v4
	s_lshr_b32 s0, s81, 29
	s_add_i32 s0, s80, s0
	s_ashr_i32 s1, s0, 3
	s_and_b32 s0, s0, -8
	s_sub_i32 s0, s80, s0
	s_cmp_lt_i32 s0, 0
	s_movk_i32 s2, 0x161
	s_cselect_b32 s2, s2, 0x160
	s_mul_i32 s0, s0, s2
	s_add_i32 s0, s0, s1
	s_mul_hi_i32 s1, s0, 0x2e8ba2e9
	s_lshr_b32 s2, s1, 31
	s_ashr_i32 s1, s1, 5
	s_add_i32 s1, s1, s2
	s_lshl_b32 s6, s1, 3
	s_mulk_i32 s1, 0xb0
	s_sub_i32 s0, s0, s1
	s_bfe_u32 s1, s0, 0x3001c
	s_add_i32 s1, s0, s1
	s_sext_i32_i16 s2, s1
	s_and_b32 s1, s1, 0xfff8
	s_sub_i32 s0, s0, s1
	s_sext_i32_i16 s0, s0
	v_lshrrev_b32_e32 v5, 2, v3
	v_lshlrev_b32_e32 v6, 1, v3
	v_and_b32_e32 v2, 0xc0, v2
	s_lshr_b32 s2, s2, 3
	s_add_i32 s8, s6, s0
	v_and_b32_e32 v5, 4, v5
	v_and_b32_e32 v6, 24, v6
	v_sub_u32_e32 v0, v0, v2
	s_ashr_i32 s9, s8, 31
	s_bfe_i64 s[6:7], s[2:3], 0x100000
	v_or3_b32 v4, v4, v5, v6
	v_lshlrev_b32_e32 v5, 5, v14
	v_ashrrev_i16_sdwa v0, v219, sext(v0) dst_sel:DWORD dst_unused:UNUSED_PAD src0_sel:DWORD src1_sel:BYTE_0
	s_lshl_b64 s[0:1], s[8:9], 19
	s_lshl_b64 s[6:7], s[6:7], 19
	v_and_b32_e32 v5, 32, v5
	v_bfe_i32 v15, v0, 0, 16
	s_add_u32 s20, s30, s6
	v_add_lshl_u32 v2, v5, v15, 1
	s_addc_u32 s21, s31, s7
	s_add_i32 s34, s18, 0
	v_lshl_add_u32 v0, v4, 11, v2
	s_add_i32 m0, s34, 0x10000
	v_lshl_add_u32 v134, v3, 11, v2
	global_load_lds_dwordx4 v0, s[20:21]
	s_add_i32 m0, s34, 0x12000
	s_add_u32 s6, s20, 0x40000
	global_load_lds_dwordx4 v130, s[20:21]
	s_addc_u32 s7, s21, 0
	s_add_i32 m0, s34, 0x14000
	v_mov_b32_e32 v131, v1
	global_load_lds_dwordx4 v0, s[6:7]
	s_add_i32 m0, s34, 0x16000
	s_add_u32 s24, s29, s0
	s_addc_u32 s25, s19, s1
	s_add_i32 s35, s34, 0x2000
	global_load_lds_dwordx4 v130, s[6:7]
	s_mov_b32 m0, s34
	s_add_u32 s0, s24, 0x40000
	global_load_lds_dwordx4 v134, s[24:25]
	s_mov_b32 m0, s35
	s_addc_u32 s1, s25, 0
	s_add_i32 s38, s34, 0x4000
	global_load_lds_dwordx4 v132, s[24:25]
	s_mov_b32 m0, s38
	s_add_i32 s39, s34, 0x6000
	global_load_lds_dwordx4 v134, s[0:1]
	s_mov_b32 m0, s39
	v_mov_b32_e32 v135, v1
	global_load_lds_dwordx4 v132, s[0:1]
	v_mov_b32_e32 v133, v1
	s_cmp_eq_u32 s4, 1
	s_mov_b32 s75, s64
	v_lshl_add_u64 v[8:9], s[20:21], 0, v[0:1]
	v_lshl_add_u64 v[6:7], s[20:21], 0, v[130:131]
	v_lshl_add_u64 v[2:3], s[24:25], 0, v[134:135]
	s_cselect_b64 s[0:1], -1, 0
	v_lshl_add_u64 v[4:5], s[24:25], 0, v[132:133]
	s_mov_b32 s101, s4
	s_lshl_b32 s5, s5, 5
	s_and_b32 s11, s5, 0x60
	s_add_i32 m0, s34, 0x18000
	v_lshl_add_u64 v[8:9], v[8:9], 0, s[22:23]
	s_lshl_b32 s10, s4, 13
	s_lshl_b32 s5, s11, 7
	global_load_lds_dwordx4 v[8:9], off
	v_lshl_add_u64 v[6:7], v[6:7], 0, s[22:23]
	s_add_i32 m0, s34, 0x1a000
	s_add_i32 s57, s34, 0x8000
	s_add_i32 s61, s34, 0xa000
	global_load_lds_dwordx4 v[6:7], off
	v_lshl_add_u64 v[2:3], v[2:3], 0, s[22:23]
	s_mov_b32 m0, s57
	s_add_u32 s6, s20, 0x40080
	global_load_lds_dwordx4 v[2:3], off
	v_lshl_add_u64 v[2:3], v[4:5], 0, s[22:23]
	s_mov_b32 m0, s61
	s_addc_u32 s7, s21, 0
	global_load_lds_dwordx4 v[2:3], off
	s_add_i32 m0, s34, 0x1c000
	v_lshl_add_u64 v[2:3], s[6:7], 0, v[0:1]
	global_load_lds_dwordx4 v[2:3], off
	v_lshl_add_u64 v[2:3], s[6:7], 0, v[130:131]
	s_add_i32 m0, s34, 0x1e000
	v_lshlrev_b32_e32 v6, 2, v166
	global_load_lds_dwordx4 v[2:3], off
	s_cmp_lg_u32 s101, 1
	s_cbranch_scc1 .LBB0_954
	s_barrier
